# attention: cross-half row-max exchange via v_permlane32_swap instead of ds_bpermute round trip
# baseline (speedup 1.0000x reference)
; DEV void attn_unit(const Params& P, int b, int qb, int h) {
;     ...
;       float mx = s0[0];
; #pragma unroll
;       for (int r = 1; r < 16; ++r) mx = fmaxf(mx, s0[r]);
; #pragma unroll
;       for (int r = 0; r < 16; ++r) mx = fmaxf(mx, s1[r]);
;       mx = fmaxf(mx, __shfl_xor(mx, 32));
;       const float mn = fmaxf(m, mx);
;       const float alpha = __builtin_amdgcn_exp2f(m - mn);
;       m = mn;
.LBB0_187:
	s_or_b64 exec, exec, s[26:27]
	s_nop 6
	v_max_f32_e32 v126, v49, v49
	v_max_f32_e32 v148, v48, v48
	v_max_f32_e32 v126, v148, v126
	v_max3_f32 v126, v126, v50, v51
	v_max3_f32 v126, v126, v52, v53
	v_max3_f32 v126, v126, v54, v55
	v_max3_f32 v126, v126, v56, v57
	v_max3_f32 v126, v126, v58, v59
	v_max3_f32 v126, v126, v60, v61
	v_max3_f32 v126, v126, v62, v63
	v_max3_f32 v126, v126, v32, v33
	v_max3_f32 v126, v126, v34, v35
	v_max3_f32 v126, v126, v36, v37
	v_max3_f32 v126, v126, v38, v39
	v_max3_f32 v126, v126, v40, v41
	v_max3_f32 v126, v126, v42, v43
	v_max3_f32 v126, v126, v44, v45
	v_max3_f32 v126, v126, v46, v47
	v_mov_b32_e32 v148, v126
	s_nop 1
	v_permlane32_swap_b32_e32 v148, v126
	v_max3_f32 v148, v125, v126, v148
	v_sub_f32_e32 v125, v125, v148
	v_exp_f32_e32 v126, v125
	s_nop 0
	v_cmp_neq_f32_e32 vcc, 1.0, v126
	s_cbranch_vccz .LBB0_182
	v_pk_mul_f32 v[14:15], v[14:15], v[126:127] op_sel_hi:[1,0]
	v_pk_mul_f32 v[12:13], v[12:13], v[126:127] op_sel_hi:[1,0]
	v_pk_mul_f32 v[10:11], v[10:11], v[126:127] op_sel_hi:[1,0]
	v_pk_mul_f32 v[8:9], v[8:9], v[126:127] op_sel_hi:[1,0]
	v_pk_mul_f32 v[6:7], v[6:7], v[126:127] op_sel_hi:[1,0]
	v_pk_mul_f32 v[4:5], v[4:5], v[126:127] op_sel_hi:[1,0]
	v_pk_mul_f32 v[2:3], v[2:3], v[126:127] op_sel_hi:[1,0]
	v_pk_mul_f32 v[0:1], v[0:1], v[126:127] op_sel_hi:[1,0]
	v_pk_mul_f32 v[30:31], v[30:31], v[126:127] op_sel_hi:[1,0]
	v_pk_mul_f32 v[28:29], v[28:29], v[126:127] op_sel_hi:[1,0]
	v_pk_mul_f32 v[26:27], v[26:27], v[126:127] op_sel_hi:[1,0]
	v_pk_mul_f32 v[24:25], v[24:25], v[126:127] op_sel_hi:[1,0]
	v_pk_mul_f32 v[22:23], v[22:23], v[126:127] op_sel_hi:[1,0]
	v_pk_mul_f32 v[20:21], v[20:21], v[126:127] op_sel_hi:[1,0]
	v_pk_mul_f32 v[18:19], v[18:19], v[126:127] op_sel_hi:[1,0]
	v_pk_mul_f32 v[16:17], v[16:17], v[126:127] op_sel_hi:[1,0]
	s_branch .LBB0_182
